# on top of previous: pconv (p -> bf16) loop unrolled x4 so all 8 loads per thread are in flight before the single wait
# baseline (speedup 1.0000x reference)
; #define GAS __attribute__((address_space(1)))
; __device__ __forceinline__ int opq_tid() { int t = threadIdx.x; asm volatile("" : "+v"(t)); return t; }
; __device__ __forceinline__ unsigned cvt_pk_bf16(float lo, float hi) { unsigned r; asm volatile("v_cvt_pk_bf16_f32 %0, %1, %2" : "=v"(r) : "v"(lo), "v"(hi)); return r; }
; __device__ __forceinline__ void pconv_phase(const GAS float* __restrict__ pin, GAS bf16_t* __restrict__ pb, int G, int cblk) {
; #pragma unroll 4
;     for (int i = cblk * 512 + opq_tid(); i < TH * PLD / 8; i += G * 512) {
;         const f32x4 a = *(const GAS f32x4*)(pin + (size_t)i * 8), b = *(const GAS f32x4*)(pin + (size_t)i * 8 + 4);
;         u32x4 w; w.x = cvt_pk_bf16(a.x, a.y); w.y = cvt_pk_bf16(a.z, a.w); w.z = cvt_pk_bf16(b.x, b.y); w.w = cvt_pk_bf16(b.z, b.w);
;         *(GAS u32x4*)(pb + (size_t)i * 8) = w;
;     }
; }
.LBB0_528:
	s_andn2_b64 vcc, exec, s[4:5]
	s_cbranch_vccnz .LBB0_799
	s_mov_b64 s[6:7], s[92:93]
	v_mov_b32_e32 v1, v242
	s_mov_b32 s2, 0x80000
	v_lshl_add_u32 v2, s75, 9, v1
	v_cmp_gt_i32_e32 vcc, s2, v2
	s_and_saveexec_b64 s[2:3], vcc
	s_cbranch_execz .LBB0_532
	s_lshl_b32 s4, s28, 23
	v_readlane_b32 s5, v254, 45
	s_add_i32 s90, s5, s4
	s_lshl_b32 s4, s77, 9
	s_waitcnt lgkmcnt(0)
	v_ashrrev_i32_e32 v3, 31, v2
	v_lshl_add_u64 v[4:5], v[2:3], 4, s[6:7]
	s_mov_b64 s[6:7], 0x9b00000
	s_ashr_i32 s5, s4, 31
	s_lshl_b64 s[8:9], s[90:91], 2
	v_lshl_add_u64 v[4:5], v[4:5], 0, s[6:7]
	s_lshl_b64 s[6:7], s[4:5], 4
	s_add_u32 s8, s95, s8
	v_lshlrev_b64 v[6:7], 5, v[2:3]
	s_addc_u32 s9, s96, s9
	v_lshl_add_u64 v[6:7], s[8:9], 0, v[6:7]
	s_lshl_b64 s[8:9], s[4:5], 5
	s_mov_b32 s5, 0x80000
.Lpc_loop:
	s_mov_b64 s[10:11], exec
	global_load_dwordx4 v[8:11], v[6:7], off offset:-16
	global_load_dwordx4 v[12:15], v[6:7], off
	v_add_u32_e32 v69, s4, v2
	v_lshl_add_u64 v[6:7], v[6:7], 0, s[8:9]
	v_cmp_gt_i32_e32 vcc, s5, v69
	v_add_u32_e32 v70, s4, v69
	v_add_u32_e32 v71, s4, v70
	s_mov_b64 exec, vcc
	global_load_dwordx4 v[44:47], v[6:7], off offset:-16
	global_load_dwordx4 v[48:51], v[6:7], off
	v_lshl_add_u64 v[6:7], v[6:7], 0, s[8:9]
	v_cmp_gt_i32_e32 vcc, s5, v70
	s_nop 1
	s_mov_b64 exec, vcc
	global_load_dwordx4 v[52:55], v[6:7], off offset:-16
	global_load_dwordx4 v[56:59], v[6:7], off
	v_lshl_add_u64 v[6:7], v[6:7], 0, s[8:9]
	v_cmp_gt_i32_e32 vcc, s5, v71
	s_nop 1
	s_mov_b64 exec, vcc
	global_load_dwordx4 v[60:63], v[6:7], off offset:-16
	global_load_dwordx4 v[64:67], v[6:7], off
	v_lshl_add_u64 v[6:7], v[6:7], 0, s[8:9]
	s_mov_b64 exec, s[10:11]
	v_add_u32_e32 v2, s4, v71
	s_waitcnt vmcnt(0)
	v_cvt_pk_bf16_f32 v8, v8, v9
	v_cvt_pk_bf16_f32 v9, v10, v11
	v_cvt_pk_bf16_f32 v10, v12, v13
	v_cvt_pk_bf16_f32 v11, v14, v15
	global_store_dwordx4 v[4:5], v[8:11], off
	v_lshl_add_u64 v[4:5], v[4:5], 0, s[6:7]
	v_cmp_gt_i32_e32 vcc, s5, v69
	s_nop 1
	s_mov_b64 exec, vcc
	v_cvt_pk_bf16_f32 v44, v44, v45
	v_cvt_pk_bf16_f32 v45, v46, v47
	v_cvt_pk_bf16_f32 v46, v48, v49
	v_cvt_pk_bf16_f32 v47, v50, v51
	global_store_dwordx4 v[4:5], v[44:47], off
	v_lshl_add_u64 v[4:5], v[4:5], 0, s[6:7]
	v_cmp_gt_i32_e32 vcc, s5, v70
	s_nop 1
	s_mov_b64 exec, vcc
	v_cvt_pk_bf16_f32 v52, v52, v53
	v_cvt_pk_bf16_f32 v53, v54, v55
	v_cvt_pk_bf16_f32 v54, v56, v57
	v_cvt_pk_bf16_f32 v55, v58, v59
	global_store_dwordx4 v[4:5], v[52:55], off
	v_lshl_add_u64 v[4:5], v[4:5], 0, s[6:7]
	v_cmp_gt_i32_e32 vcc, s5, v71
	s_nop 1
	s_mov_b64 exec, vcc
	v_cvt_pk_bf16_f32 v60, v60, v61
	v_cvt_pk_bf16_f32 v61, v62, v63
	v_cvt_pk_bf16_f32 v62, v64, v65
	v_cvt_pk_bf16_f32 v63, v66, v67
	global_store_dwordx4 v[4:5], v[60:63], off
	v_lshl_add_u64 v[4:5], v[4:5], 0, s[6:7]
	v_cmp_gt_i32_e32 vcc, s5, v2
	s_nop 1
	s_mov_b64 exec, vcc
	s_cbranch_execnz .Lpc_loop
